# v3 + helper prefetch landing/deferred wait (chain4)
# speedup vs baseline: 1.0110x; 1.0110x over previous
.LBB0_893:
	s_or_b64 exec, exec, s[34:35]
	s_lshr_b32 s34, s15, 2
	s_and_b32 s34, s34, 7
	s_lshl_b32 s52, s34, 2
	v_lshlrev_b32_e32 v0, 1, v102
	s_cmp_eq_u32 s44, 0
	v_lshl_or_b32 v12, s34, 7, v0
	s_cselect_b64 s[72:73], -1, 0
	s_lshl_b32 s34, s15, 3
	s_and_b32 s34, s34, 0xf8
	s_add_u32 s74, s22, s34
	s_addc_u32 s75, s23, 0
	s_lshl_b32 s44, s33, 1
	s_add_u32 s44, s0, s44
	s_addc_u32 s47, s1, 0
	s_lshl_b32 s46, s37, 1
	s_add_u32 s46, s44, s46
	s_addc_u32 s47, s47, 0
	v_lshlrev_b32_e32 v0, 1, v80
	s_lshl_b64 s[50:51], s[76:77], 17
	v_lshl_add_u64 v[72:73], s[46:47], 0, v[0:1]
	v_lshlrev_b64 v[74:75], 1, v[10:11]
	s_lshl_b64 s[46:47], s[76:77], 22
	s_or_b32 s50, s50, s52
	s_waitcnt vmcnt(0) lgkmcnt(0)
	v_mov_b32_e32 v70, v19
	v_mov_b32_e32 v71, v3
	v_mov_b32_e32 v19, v2
	v_lshl_add_u64 v[76:77], v[82:83], 0, s[46:47]
	v_lshl_add_u64 v[92:93], v[84:85], 0, s[50:51]
	v_lshl_add_u64 v[94:95], v[86:87], 0, s[46:47]
	s_mul_hi_i32 s44, s76, 0x2e80000
	s_mul_i32 s50, s76, 0x2e80000
	v_mad_i64_i32 v[2:3], s[46:47], s76, v210, v[74:75]
	v_lshl_add_u64 v[96:97], v[90:91], 0, v[2:3]
	v_or_b32_e32 v2, s50, v12
	v_mov_b32_e32 v3, s44
	s_mov_b32 s35, s45
	v_mov_b32_e32 v64, v25
	v_mov_b32_e32 v65, v9
	v_mov_b32_e32 v25, v8
	v_mov_b32_e32 v66, v23
	v_mov_b32_e32 v67, v7
	v_mov_b32_e32 v23, v6
	v_mov_b32_e32 v68, v21
	v_mov_b32_e32 v69, v5
	v_mov_b32_e32 v21, v4
	v_lshl_add_u64 v[98:99], v[88:89], 0, v[2:3]
	s_mov_b32 s47, -1
	s_mov_b64 s[76:77], 0
	s_movk_i32 s44, 0xffc0
	v_mov_b64_e32 v[196:197], v[60:61]
	v_mov_b64_e32 v[184:185], v[56:57]
	v_mov_b64_e32 v[188:189], v[48:49]
	v_mov_b64_e32 v[192:193], v[52:53]
	v_mov_b64_e32 v[194:195], v[58:59]
	v_mov_b64_e32 v[182:183], v[54:55]
	v_mov_b64_e32 v[186:187], v[46:47]
	v_mov_b64_e32 v[190:191], v[50:51]
	s_branch .LBB0_896

.LBB0_895:
	s_add_u32 s76, s76, 0x5d000
	s_addc_u32 s77, s77, 0
	s_add_i32 s44, s44, 32
	s_mov_b64 s[50:51], 0x400
	s_waitcnt lgkmcnt(0)
	s_nop 0
	s_nop 0
	s_nop 0
	s_nop 0
	v_lshl_add_u64 v[76:77], v[76:77], 0, s[56:57]
	v_lshl_add_u64 v[92:93], v[92:93], 0, s[50:51]
	v_lshl_add_u64 v[94:95], v[94:95], 0, s[56:57]
	s_cmp_eq_u32 s76, 0x2edd000
	s_nop 0
	s_nop 0
	s_nop 0
	s_nop 0
	s_mov_b32 s47, s46
	s_barrier
	s_cbranch_scc1 .LBB0_917
.LBB0_896:
	s_cmp_lt_i32 s47, 1
	s_cbranch_scc1 .LBB0_900
	s_and_b32 s46, s44, 32
	v_lshl_add_u32 v4, s46, 7, v104
	ds_read2_b64 v[4:7], v4 offset1:2
	v_add_u32_e32 v8, s46, v78
	v_lshl_add_u32 v9, v8, 3, s16
	v_lshl_add_u32 v10, v8, 6, v105
	ds_read2_b32 v[8:9], v9 offset1:1
	ds_read_b64 v[10:11], v10
	s_waitcnt lgkmcnt(2)
	v_mov_b32_e32 v14, v5
	v_mov_b32_e32 v15, v7
	v_mov_b32_e32 v5, v6
	v_lshl_add_u64 v[2:3], v[62:63], 0, s[44:45]
	s_waitcnt lgkmcnt(1)
	v_pk_fma_f32 v[4:5], v[14:15], v[8:9], v[4:5] op_sel_hi:[1,0,1]
	v_mad_u64_u32 v[12:13], s[50:51], v2, s95, v[72:73]
	s_waitcnt lgkmcnt(0)
	v_pk_fma_f32 v[4:5], v[8:9], v[10:11], v[4:5] op_sel:[1,0,0]
	v_mad_i32_i24 v13, v3, s95, v13
	v_cvt_pk_bf16_f32 v6, v4, v5
	global_store_dword v[12:13], v6, off offset:1024
	v_pk_mul_f32 v[6:7], v[4:5], v[4:5]
	v_mov_b32_e32 v8, v4
	v_mov_b32_e32 v9, v6
	v_mov_b32_e32 v6, v5
	v_pk_add_f32 v[4:5], v[8:9], v[6:7]
	s_nop 1
	v_mov_b32_dpp v6, v4 row_half_mirror row_mask:0xf bank_mask:0xf bound_ctrl:1
	v_mov_b32_dpp v7, v5 row_half_mirror row_mask:0xf bank_mask:0xf bound_ctrl:1
	v_pk_add_f32 v[4:5], v[4:5], v[6:7]
	s_nop 1
	v_mov_b32_dpp v6, v4 quad_perm:[1,0,3,2] row_mask:0xf bank_mask:0xf bound_ctrl:1
	v_mov_b32_dpp v7, v5 quad_perm:[1,0,3,2] row_mask:0xf bank_mask:0xf bound_ctrl:1
	v_pk_add_f32 v[4:5], v[4:5], v[6:7]
	s_nop 1
	v_mov_b32_dpp v6, v4 quad_perm:[2,3,0,1] row_mask:0xf bank_mask:0xf bound_ctrl:1
	v_mov_b32_dpp v7, v5 quad_perm:[2,3,0,1] row_mask:0xf bank_mask:0xf bound_ctrl:1
	s_and_saveexec_b64 s[78:79], s[10:11]
	s_cbranch_execz .LBB0_899
	v_lshlrev_b64 v[2:3], 8, v[2:3]
	v_lshl_add_u64 v[2:3], s[74:75], 0, v[2:3]
	v_pk_add_f32 v[4:5], v[4:5], v[6:7]
	global_store_dwordx2 v[2:3], v[4:5], off

.LBB0_900:
	s_add_i32 s46, s47, 1
	s_cmpk_gt_i32 s47, 0x7e
	s_cbranch_scc1 .LBB0_912
	s_waitcnt vmcnt(0)
	v_mov_b64_e32 v[60:61], v[196:197]
	v_mov_b64_e32 v[56:57], v[184:185]
	v_mov_b64_e32 v[48:49], v[188:189]
	v_mov_b64_e32 v[52:53], v[192:193]
	v_mov_b64_e32 v[58:59], v[194:195]
	v_mov_b64_e32 v[54:55], v[182:183]
	v_mov_b64_e32 v[46:47], v[186:187]
	v_mov_b64_e32 v[50:51], v[190:191]
	s_and_b32 s47, s46, 1
	s_and_saveexec_b64 s[78:79], s[6:7]
	s_cbranch_execz .LBB0_907
	v_lshlrev_b32_e32 v2, 16, v34
	v_and_b32_e32 v3, 0xffff0000, v34
	v_lshlrev_b32_e32 v4, 16, v35
	v_and_b32_e32 v5, 0xffff0000, v35
	v_lshlrev_b32_e32 v6, 16, v36
	v_and_b32_e32 v7, 0xffff0000, v36
	v_lshlrev_b32_e32 v8, 16, v37
	v_and_b32_e32 v9, 0xffff0000, v37
	s_and_b64 vcc, exec, s[12:13]
	s_mov_b64 s[80:81], -1
	s_cbranch_vccnz .LBB0_904
	v_lshlrev_b32_e32 v10, 16, v42
	v_and_b32_e32 v11, 0xffff0000, v42
	v_lshlrev_b32_e32 v12, 16, v38
	v_and_b32_e32 v13, 0xffff0000, v38
	v_pk_add_f32 v[10:11], v[10:11], v[2:3] neg_lo:[0,1] neg_hi:[0,1]
	v_lshlrev_b32_e32 v14, 16, v39
	v_pk_fma_f32 v[10:11], v[10:11], v[12:13], v[2:3]
	v_lshlrev_b32_e32 v12, 16, v43
	v_and_b32_e32 v13, 0xffff0000, v43
	v_and_b32_e32 v15, 0xffff0000, v39
	v_pk_add_f32 v[12:13], v[12:13], v[4:5] neg_lo:[0,1] neg_hi:[0,1]
	v_lshlrev_b32_e32 v16, 16, v40
	v_pk_fma_f32 v[12:13], v[12:13], v[14:15], v[4:5]
	v_lshlrev_b32_e32 v14, 16, v44
	v_and_b32_e32 v15, 0xffff0000, v44
	v_and_b32_e32 v17, 0xffff0000, v40
	v_pk_add_f32 v[14:15], v[14:15], v[6:7] neg_lo:[0,1] neg_hi:[0,1]
	v_lshlrev_b32_e32 v110, 16, v41
	v_pk_fma_f32 v[16:17], v[14:15], v[16:17], v[6:7]
	v_lshlrev_b32_e32 v14, 16, v45
	v_and_b32_e32 v15, 0xffff0000, v45
	v_and_b32_e32 v111, 0xffff0000, v41
	v_pk_add_f32 v[14:15], v[14:15], v[8:9] neg_lo:[0,1] neg_hi:[0,1]
	s_mov_b32 s50, 0x2bf0000
	v_pk_fma_f32 v[110:111], v[14:15], v[110:111], v[8:9]
	v_cvt_pk_bf16_f32 v14, v10, v11
	v_lshl_add_u64 v[10:11], v[76:77], 0, v[74:75]
	v_add_co_u32_e32 v10, vcc, s50, v10
	v_cvt_pk_bf16_f32 v15, v12, v13
	v_cvt_pk_bf16_f32 v16, v16, v17
	v_cvt_pk_bf16_f32 v17, v110, v111
	v_addc_co_u32_e32 v11, vcc, 0, v11, vcc
	global_store_dwordx4 v[10:11], v[14:17], off
	v_lshlrev_b32_e32 v10, 16, v14
	v_and_b32_e32 v11, 0xffff0000, v14
	v_lshlrev_b32_e32 v12, 16, v15
	v_and_b32_e32 v13, 0xffff0000, v15
	v_lshlrev_b32_e32 v14, 16, v16
	v_and_b32_e32 v15, 0xffff0000, v16
	v_lshlrev_b32_e32 v16, 16, v17
	v_and_b32_e32 v17, 0xffff0000, v17
	s_mov_b64 s[80:81], 0
.LBB0_904:
	s_andn2_b64 vcc, exec, s[80:81]
	s_cbranch_vccnz .LBB0_906
	v_lshl_add_u64 v[10:11], v[76:77], 0, v[74:75]
	v_add_co_u32_e32 v10, vcc, 0x2bf0000, v10
	s_nop 1
	v_addc_co_u32_e32 v11, vcc, 0, v11, vcc
	global_store_dwordx4 v[10:11], v[34:37], off
	v_mov_b64_e32 v[16:17], v[8:9]
	v_mov_b64_e32 v[14:15], v[6:7]
	v_mov_b64_e32 v[12:13], v[4:5]
	v_mov_b64_e32 v[10:11], v[2:3]

.LBB0_907:
	s_or_b64 exec, exec, s[78:79]
	s_cmp_eq_u32 s76, 0x2e23000
	s_cbranch_scc1 .LBB0_913
	v_lshl_add_u64 v[2:3], v[98:99], 0, s[76:77]
	v_add_co_u32_e32 v10, vcc, 0x8c4e000, v2
	s_nop 1
	v_addc_co_u32_e32 v11, vcc, 0, v3, vcc
	v_add_co_u32_e32 v6, vcc, 0x8c4d000, v2
	s_nop 1
	v_addc_co_u32_e32 v7, vcc, 0, v3, vcc
	global_load_dwordx4 v[182:185], v[6:7], off offset:2048
	s_nop 0
	global_load_dwordx4 v[186:189], v[6:7], off offset:3072
	s_nop 0
	global_load_dwordx4 v[194:197], v[10:11], off
	s_nop 0
	global_load_dwordx4 v[190:193], v[10:11], off offset:1024
	s_and_saveexec_b64 s[78:79], s[6:7]
	s_cbranch_execz .LBB0_911
	v_lshl_add_u64 v[34:35], v[96:97], 0, s[76:77]
	global_load_dwordx4 v[34:37], v[34:35], off
	s_and_b64 vcc, exec, s[12:13]
	s_cbranch_vccnz .LBB0_911
	v_lshl_add_u64 v[38:39], v[76:77], 0, v[74:75]
	v_add_co_u32_e32 v38, vcc, 0x2bf8000, v38
	v_lshl_add_u64 v[40:41], v[94:95], 0, v[74:75]
	s_nop 0
	v_addc_co_u32_e32 v39, vcc, 0, v39, vcc
	global_load_dwordx4 v[42:45], v[38:39], off
	s_nop 0
	global_load_dwordx4 v[38:41], v[40:41], off

.LBB0_914:
	v_lshlrev_b32_e32 v112, 16, v59
	v_and_b32_e32 v118, 0xffff0000, v59
	v_lshlrev_b32_e32 v59, 16, v54
	v_lshlrev_b32_e32 v120, 16, v60
	v_and_b32_e32 v122, 0xffff0000, v60
	v_and_b32_e32 v60, 0xffff0000, v54
	v_lshlrev_b32_e32 v127, 16, v50
	v_lshlrev_b32_e32 v126, 16, v46
	v_and_b32_e32 v131, 0xffff0000, v50
	v_and_b32_e32 v130, 0xffff0000, v46
	v_lshlrev_b32_e32 v46, 16, v48
	v_and_b32_e32 v50, 0xffff0000, v48
	v_mul_f32_e32 v48, 0x3fb8aa3b, v59
	v_lshlrev_b32_e32 v124, 16, v61
	v_and_b32_e32 v134, 0xffff0000, v61
	v_lshlrev_b32_e32 v61, 16, v55
	v_exp_f32_e32 v54, v48
	v_mul_f32_e32 v48, 0x3fb8aa3b, v60
	v_and_b32_e32 v109, 0xffff0000, v55
	v_exp_f32_e32 v55, v48
	v_mul_f32_e32 v48, 0x3fb8aa3b, v61
	v_lshlrev_b32_e32 v113, 16, v56
	v_and_b32_e32 v115, 0xffff0000, v56
	v_exp_f32_e32 v56, v48
	v_mul_f32_e32 v48, 0x3fb8aa3b, v109
	v_lshlrev_b32_e32 v116, 16, v57
	v_and_b32_e32 v121, 0xffff0000, v57
	v_exp_f32_e32 v57, v48
	v_mul_f32_e32 v48, 0x3fb8aa3b, v113
	v_and_b32_e32 v128, 0xffff0000, v47
	v_lshlrev_b32_e32 v133, 16, v51
	v_lshlrev_b32_e32 v132, 16, v47
	v_and_b32_e32 v129, 0xffff0000, v51
	v_exp_f32_e32 v114, v48
	v_mul_f32_e32 v48, 0x3fb8aa3b, v115
	v_lshlrev_b32_e32 v47, 16, v52
	v_and_b32_e32 v51, 0xffff0000, v52
	v_lshlrev_b32_e32 v136, 16, v49
	v_and_b32_e32 v52, 0xffff0000, v49
	v_add_f32_e32 v49, -1.0, v126
	v_add_f32_e32 v141, -1.0, v132
	v_add_f32_e32 v143, -1.0, v128
	v_exp_f32_e32 v115, v48
	v_mov_b32_e32 v142, v129
	v_mov_b32_e32 v140, v133
	v_mov_b32_e32 v48, v127
	v_add_f32_e32 v139, -1.0, v130
	v_pk_mul_f32 v[162:163], v[68:69], v[142:143]
	v_pk_mul_f32 v[164:165], v[20:21], v[140:141]
	v_mov_b32_e32 v138, v131
	v_pk_mul_f32 v[170:171], v[18:19], v[48:49]
	v_add_f32_e32 v145, -1.0, v46
	v_add_f32_e32 v147, -1.0, v50
	v_mov_b32_e32 v146, v51
	v_mov_b32_e32 v144, v47
	v_mov_b32_e32 v166, v162
	v_mov_b32_e32 v167, v164
	v_pk_mul_f32 v[168:169], v[70:71], v[138:139]
	v_mul_f32_e32 v109, v170, v170
	v_lshlrev_b32_e32 v137, 16, v53
	v_and_b32_e32 v53, 0xffff0000, v53
	v_pk_mul_f32 v[156:157], v[66:67], v[146:147]
	v_pk_mul_f32 v[158:159], v[22:23], v[144:145]
	v_pk_mul_f32 v[166:167], v[166:167], v[166:167]
	v_fmac_f32_e32 v109, v168, v168
	v_add_f32_e32 v149, -1.0, v136
	v_add_f32_e32 v151, -1.0, v52
	v_mov_b32_e32 v150, v53
	v_mov_b32_e32 v148, v137
	v_mov_b32_e32 v160, v156
	v_mov_b32_e32 v161, v158
	v_add_f32_e32 v109, v167, v109
	v_pk_mul_f32 v[152:153], v[64:65], v[150:151]
	v_pk_mul_f32 v[154:155], v[24:25], v[148:149]
	v_pk_mul_f32 v[160:161], v[160:161], v[160:161]
	v_add_f32_e32 v109, v166, v109
	v_mul_f32_e32 v60, 0x3fb8aa3b, v116
	v_mov_b32_e32 v116, v152
	v_mov_b32_e32 v117, v154
	v_add_f32_e32 v109, v161, v109
	v_pk_mul_f32 v[116:117], v[116:117], v[116:117]
	v_add_f32_e32 v109, v160, v109
	v_add_f32_e32 v109, v117, v109
	v_add_f32_e32 v109, v116, v109
	v_exp_f32_e32 v116, v60
	v_mul_f32_e32 v60, 0x3fb8aa3b, v121
	v_add_f32_dpp v109, v109, v109 row_half_mirror row_mask:0xf bank_mask:0xf bound_ctrl:1
	v_exp_f32_e32 v117, v60
	v_pk_fma_f32 v[48:49], v[18:19], v[48:49], s[16:17]
	v_add_f32_dpp v109, v109, v109 quad_perm:[1,0,3,2] row_mask:0xf bank_mask:0xf bound_ctrl:1
	v_lshlrev_b32_e32 v110, 16, v58
	v_and_b32_e32 v58, 0xffff0000, v58
	v_add_f32_dpp v109, v109, v109 quad_perm:[2,3,0,1] row_mask:0xf bank_mask:0xf bound_ctrl:1
	v_sqrt_f32_e32 v109, v109
	v_mul_f32_e32 v59, v54, v110
	v_mul_f32_e32 v113, v57, v118
	v_mul_f32_e32 v111, v56, v112
	v_max_f32_e32 v60, 0x2b8cbccc, v109
	v_rcp_f32_e32 v178, v60
	v_mul_f32_e32 v119, v114, v120
	v_mul_f32_e32 v121, v115, v122
	v_mul_f32_e32 v123, v116, v124
	v_pk_mul_f32 v[160:161], v[170:171], v[178:179]
	v_pk_mul_f32 v[168:169], v[168:169], v[178:179]
	v_mov_b32_e32 v161, v49
	v_pk_mul_f32 v[166:167], v[160:161], v[126:127]
	v_pk_fma_f32 v[126:127], v[70:71], v[138:139], s[16:17]
	v_mul_f32_e32 v48, v167, v110
	v_mov_b32_e32 v169, v127
	v_pk_mul_f32 v[126:127], v[168:169], v[130:131]
	v_fma_f32 v109, v26, v48, 0
	v_pk_mul_f32 v[130:131], v[126:127], v[58:59] op_sel_hi:[1,0]
	v_pk_mul_f32 v[138:139], v[164:165], v[178:179]
	v_fmac_f32_e32 v109, v27, v131
	v_pk_fma_f32 v[130:131], v[20:21], v[140:141], s[16:17]
	v_pk_fma_f32 v[48:49], v[166:167], v[110:111], 0 op_sel_hi:[1,0,0]
	v_mov_b32_e32 v139, v131
	v_pk_mul_f32 v[140:141], v[138:139], v[132:133]
	v_pk_fma_f32 v[132:133], v[68:69], v[142:143], s[16:17]
	v_pk_mul_f32 v[130:131], v[140:141], v[112:113] op_sel_hi:[1,0]
	v_pk_fma_f32 v[48:49], v[126:127], v[58:59], v[48:49] op_sel_hi:[1,0,1]
	v_fmac_f32_e32 v109, v28, v131
	v_pk_mul_f32 v[130:131], v[162:163], v[178:179]
	v_pk_fma_f32 v[48:49], v[140:141], v[112:113], v[48:49] op_sel_hi:[1,0,1]
	v_mov_b32_e32 v131, v133
	v_pk_mul_f32 v[128:129], v[130:131], v[128:129]
	v_xor_b32_e32 v112, 0x80000000, v130
	v_pk_mul_f32 v[130:131], v[128:129], v[118:119] op_sel_hi:[1,0]
	v_pk_mul_f32 v[142:143], v[158:159], v[178:179]
	v_fmac_f32_e32 v109, v29, v131
	v_pk_fma_f32 v[130:131], v[22:23], v[144:145], s[16:17]
	v_pk_fma_f32 v[48:49], v[128:129], v[118:119], v[48:49] op_sel_hi:[1,0,1]
	v_mov_b32_e32 v143, v131
	v_pk_mul_f32 v[144:145], v[142:143], v[46:47]
	v_pk_fma_f32 v[130:131], v[66:67], v[146:147], s[16:17]
	v_pk_mul_f32 v[46:47], v[144:145], v[120:121] op_sel_hi:[1,0]
	v_pk_fma_f32 v[48:49], v[144:145], v[120:121], v[48:49] op_sel_hi:[1,0,1]
	v_fmac_f32_e32 v109, v30, v47
	v_pk_mul_f32 v[46:47], v[156:157], v[178:179]
	v_pk_mul_f32 v[146:147], v[154:155], v[178:179]
	v_mov_b32_e32 v47, v131
	v_pk_mul_f32 v[130:131], v[46:47], v[50:51]
	v_xor_b32_e32 v120, 0x80000000, v46
	v_pk_mul_f32 v[46:47], v[130:131], v[122:123] op_sel_hi:[1,0]
	v_mul_f32_e32 v125, v117, v134
	v_fmac_f32_e32 v109, v31, v47
	v_pk_fma_f32 v[46:47], v[24:25], v[148:149], s[16:17]
	v_pk_fma_f32 v[50:51], v[64:65], v[150:151], s[16:17]
	v_mov_b32_e32 v147, v47
	v_pk_mul_f32 v[136:137], v[146:147], v[136:137]
	v_pk_fma_f32 v[48:49], v[130:131], v[122:123], v[48:49] op_sel_hi:[1,0,1]
	v_pk_mul_f32 v[46:47], v[136:137], v[124:125] op_sel_hi:[1,0]
	v_pk_fma_f32 v[48:49], v[136:137], v[124:125], v[48:49] op_sel_hi:[1,0,1]
	v_fmac_f32_e32 v109, v32, v47
	v_pk_mul_f32 v[46:47], v[152:153], v[178:179]
	v_mul_f32_e32 v61, v55, v58
	v_mov_b32_e32 v47, v51
	v_pk_mul_f32 v[132:133], v[46:47], v[52:53]
	v_xor_b32_e32 v124, 0x80000000, v46
	v_pk_mul_f32 v[46:47], v[132:133], v[134:135] op_sel_hi:[1,0]
	v_pk_fma_f32 v[48:49], v[132:133], v[134:135], v[48:49] op_sel_hi:[1,0,1]
	v_lshl_add_u32 v52, s47, 5, v78
	v_fmac_f32_e32 v109, v33, v47
	v_mov_b32_dpp v46, v48 row_half_mirror row_mask:0xf bank_mask:0xf bound_ctrl:1
	v_mov_b32_dpp v47, v49 row_half_mirror row_mask:0xf bank_mask:0xf bound_ctrl:1
	v_lshl_or_b32 v53, v52, 4, v80
	v_pk_add_f32 v[46:47], v[48:49], v[46:47]
	v_mul_lo_u32 v53, v53, s42
	v_xor_b32_e32 v60, 0x80000000, v168
	v_mov_b32_dpp v48, v46 quad_perm:[1,0,3,2] row_mask:0xf bank_mask:0xf bound_ctrl:1
	v_mov_b32_dpp v49, v47 quad_perm:[1,0,3,2] row_mask:0xf bank_mask:0xf bound_ctrl:1
	v_add_f32_dpp v50, v109, v109 row_half_mirror row_mask:0xf bank_mask:0xf bound_ctrl:1
	v_add_u32_e32 v53, s14, v53
	v_xor_b32_e32 v58, 0x80000000, v160
	v_xor_b32_e32 v110, 0x80000000, v138
	v_pk_add_f32 v[46:47], v[46:47], v[48:49]
	v_add_f32_dpp v50, v50, v50 quad_perm:[1,0,3,2] row_mask:0xf bank_mask:0xf bound_ctrl:1
	v_and_b32_e32 v172, 4, v200
	v_cmp_ne_u32_e64 s[100:101], 0, v172
	s_nop 1
	v_cndmask_b32_e64 v172, v58, v59, s[100:101]
	v_cndmask_b32_e64 v173, v59, v58, s[100:101]
	v_cndmask_b32_e64 v174, v60, v61, s[100:101]
	v_cndmask_b32_e64 v175, v61, v60, s[100:101]
	ds_write_b128 v53, v[172:175]
	v_cndmask_b32_e64 v172, v110, v111, s[100:101]
	v_cndmask_b32_e64 v173, v111, v110, s[100:101]
	v_cndmask_b32_e64 v174, v112, v113, s[100:101]
	v_cndmask_b32_e64 v175, v113, v112, s[100:101]
	ds_write_b128 v53, v[172:175] offset:16
	ds_write_b128 v53, v[54:57] offset:32
	v_mov_b32_e32 v54, v166
	v_mov_b32_e32 v55, v126
	v_mov_b32_e32 v56, v140
	v_mov_b32_e32 v57, v128
	v_mov_b32_dpp v48, v46 quad_perm:[2,3,0,1] row_mask:0xf bank_mask:0xf bound_ctrl:1
	v_mov_b32_dpp v49, v47 quad_perm:[2,3,0,1] row_mask:0xf bank_mask:0xf bound_ctrl:1
	v_mov_b32_dpp v51, v50 quad_perm:[2,3,0,1] row_mask:0xf bank_mask:0xf bound_ctrl:1
	ds_write_b128 v53, v[54:57] offset:48
	v_mov_b32_e32 v126, v167
	v_mov_b32_e32 v128, v141
	v_xor_b32_e32 v118, 0x80000000, v142
	v_xor_b32_e32 v122, 0x80000000, v146
	v_mov_b32_e32 v54, v144
	v_mov_b32_e32 v55, v130
	v_mov_b32_e32 v56, v136
	v_mov_b32_e32 v57, v132
	v_mov_b32_e32 v130, v145
	v_mov_b32_e32 v132, v137
	ds_write_b128 v53, v[126:129] offset:64
	v_cndmask_b32_e64 v172, v118, v119, s[100:101]
	v_cndmask_b32_e64 v173, v119, v118, s[100:101]
	v_cndmask_b32_e64 v174, v120, v121, s[100:101]
	v_cndmask_b32_e64 v175, v121, v120, s[100:101]
	ds_write_b128 v53, v[172:175] offset:80
	v_cndmask_b32_e64 v172, v122, v123, s[100:101]
	v_cndmask_b32_e64 v173, v123, v122, s[100:101]
	v_cndmask_b32_e64 v174, v124, v125, s[100:101]
	v_cndmask_b32_e64 v175, v125, v124, s[100:101]
	ds_write_b128 v53, v[172:175] offset:96
	ds_write_b128 v53, v[114:117] offset:112
	ds_write_b128 v53, v[54:57] offset:128
	ds_write_b128 v53, v[130:133] offset:144
	s_and_saveexec_b64 s[78:79], s[10:11]
	s_cbranch_execz .LBB0_894
	v_lshl_add_u32 v52, v52, 3, s16
	v_pk_add_f32 v[46:47], v[46:47], v[48:49]
	s_andn2_b64 vcc, exec, s[72:73]
	ds_write2_b32 v52, v46, v47 offset1:1
	s_cbranch_vccnz .LBB0_894
	v_add_f32_e32 v46, v50, v51
	global_store_dword v[92:93], v46, off
	s_branch .LBB0_894
.LBB0_917:
	v_add_u32_e32 v4, 0x1000, v104
	ds_read2_b64 v[4:7], v4 offset1:2
	ds_read2_b32 v[8:9], v107 offset1:1
	ds_read_b64 v[10:11], v108
	s_mov_b64 s[12:13], 0xfe0
	v_lshl_add_u64 v[2:3], v[62:63], 0, s[12:13]
	v_mov_b64_e32 v[12:13], s[0:1]
	s_waitcnt lgkmcnt(2)
	v_mov_b32_e32 v14, v5
	v_mov_b32_e32 v15, v7
	v_mov_b32_e32 v5, v6
	v_mad_u64_u32 v[12:13], s[12:13], v2, s95, v[12:13]
	s_waitcnt lgkmcnt(1)
	v_pk_fma_f32 v[4:5], v[14:15], v[8:9], v[4:5] op_sel_hi:[1,0,1]
	v_mad_i32_i24 v13, v3, s95, v13
	s_lshl_b32 s44, s33, 1
	s_waitcnt lgkmcnt(0)
	v_pk_fma_f32 v[4:5], v[8:9], v[10:11], v[4:5] op_sel:[1,0,0]
	v_lshl_add_u64 v[12:13], v[12:13], 0, s[44:45]
	s_lshl_b32 s44, s37, 1
	v_pk_mul_f32 v[6:7], v[4:5], v[4:5]
	v_lshl_add_u64 v[12:13], v[12:13], 0, s[44:45]
	v_mov_b32_e32 v8, v4
	v_mov_b32_e32 v9, v6
	v_mov_b32_e32 v6, v5
	v_lshl_add_u64 v[12:13], v[12:13], 0, v[0:1]
	v_cvt_pk_bf16_f32 v0, v4, v5
	v_pk_add_f32 v[4:5], v[8:9], v[6:7]
	global_store_dword v[12:13], v0, off offset:1024
	s_nop 0
	v_mov_b32_dpp v6, v4 row_half_mirror row_mask:0xf bank_mask:0xf bound_ctrl:1
	v_mov_b32_dpp v7, v5 row_half_mirror row_mask:0xf bank_mask:0xf bound_ctrl:1
	v_pk_add_f32 v[4:5], v[4:5], v[6:7]
	s_nop 1
	v_mov_b32_dpp v6, v4 quad_perm:[1,0,3,2] row_mask:0xf bank_mask:0xf bound_ctrl:1
	v_mov_b32_dpp v7, v5 quad_perm:[1,0,3,2] row_mask:0xf bank_mask:0xf bound_ctrl:1
	v_pk_add_f32 v[4:5], v[4:5], v[6:7]
	s_nop 1
	v_mov_b32_dpp v6, v4 quad_perm:[2,3,0,1] row_mask:0xf bank_mask:0xf bound_ctrl:1
	v_mov_b32_dpp v7, v5 quad_perm:[2,3,0,1] row_mask:0xf bank_mask:0xf bound_ctrl:1
	s_and_saveexec_b64 s[12:13], s[10:11]
	s_cbranch_execz .LBB0_848
	v_lshlrev_b64 v[2:3], 8, v[2:3]
	v_lshl_add_u64 v[2:3], s[22:23], 0, v[2:3]
	v_lshl_add_u64 v[2:3], v[2:3], 0, s[34:35]
	v_pk_add_f32 v[4:5], v[4:5], v[6:7]
	global_store_dwordx2 v[2:3], v[4:5], off
	s_branch .LBB0_848
